# v83 + attention: static priority 2 for waves 0..3 (critical lower rows), waves 4..7 fill gaps
# baseline (speedup 1.0000x reference)
.LBB0_1330:
	s_or_b64 exec, exec, s[6:7]
	v_mov_b32_e32 v1, v192
	s_waitcnt lgkmcnt(0)
	s_barrier
	s_cmpk_gt_i32 s2, 0x1ff
	v_readfirstlane_b32 s6, v1
	s_cbranch_scc1 .LBB0_1349
	v_ashrrev_i32_e32 v193, 4, v1
	v_add_u32_e32 v194, 32, v193
	s_ashr_i32 s10, s6, 6
	s_cmp_lt_u32 s6, 0x100
	s_cbranch_scc0 .Lattn_prio_lo
	s_setprio 2
.Lattn_prio_lo:
	v_and_b32_e32 v7, 0xfffff0, v193
	v_lshlrev_b32_e32 v8, 1, v193
	v_and_b32_e32 v10, 0xfffff0, v194
	s_waitcnt vmcnt(14)
	v_lshlrev_b32_e32 v12, 1, v194
	v_and_b32_e32 v3, 63, v1
	v_and_b32_e32 v187, 31, v1
	s_lshl_b32 s22, s10, 5
	v_lshlrev_b32_e32 v6, 3, v1
	v_and_or_b32 v7, v8, 8, v7
	v_and_or_b32 v10, v12, 8, v10
	v_or_b32_e32 v0, s22, v187
	s_movk_i32 s23, 0x3000
	v_and_b32_e32 v4, 0x78, v6
	v_lshrrev_b32_e32 v8, 1, v193
	v_lshrrev_b32_e32 v7, 1, v7
	v_bfe_u32 v6, v6, 5, 2
	v_and_b32_e32 v9, 3, v193
	v_lshrrev_b32_e32 v10, 1, v10
	v_lshlrev_b32_e32 v12, 4, v3
	v_mad_i64_i32 v[160:161], s[6:7], v0, s23, 0
	v_or_b32_e32 v7, v7, v6
	v_and_or_b32 v8, v8, 4, v9
	v_or_b32_e32 v6, v10, v6
	v_lshlrev_b32_e32 v10, 3, v3
	v_and_b32_e32 v13, 0xc0, v12
	v_lshlrev_b32_e32 v14, 1, v1
	v_bfe_u32 v5, v1, 5, 1
	v_and_or_b32 v13, v10, 24, v13
	v_and_b32_e32 v14, 32, v14
	v_and_b32_e32 v10, 0x100, v10
	s_lshl_b32 s7, s10, 2
	v_lshl_add_u32 v8, v8, 6, 0
	v_lshlrev_b32_e32 v9, 1, v4
	v_or3_b32 v10, v13, v14, v10
	s_add_i32 s24, s7, 0
	v_lshl_add_u32 v13, v6, 9, v8
	s_movk_i32 s7, 0x70
	v_lshlrev_b32_e32 v6, 4, v5
	v_and_b32_e32 v11, 48, v9
	v_lshl_add_u32 v7, v7, 9, v8
	v_bitop3_b32 v9, v9, v1, s7 bitop3:0x78
	v_and_b32_e32 v8, 0x70, v12
	s_waitcnt vmcnt(12)
	v_bitop3_b32 v21, v6, v12, s7 bitop3:0x78
	s_movk_i32 s7, 0x60
	s_movk_i32 s6, 0xc0
	s_waitcnt vmcnt(11)
	v_bitop3_b32 v25, v6, v8, s7 bitop3:0x36
	s_movk_i32 s7, 0x80
	v_bitop3_b32 v26, v6, v8, s7 bitop3:0x36
	s_movk_i32 s7, 0xa0
	s_waitcnt vmcnt(10)
	v_bitop3_b32 v28, v6, v8, s6 bitop3:0x36
	s_movk_i32 s6, 0xe0
	s_mulk_i32 s10, 0x2200
	v_lshlrev_b32_e32 v2, 3, v5
	v_bitop3_b32 v27, v6, v8, s7 bitop3:0x36
	v_bitop3_b32 v29, v6, v8, s6 bitop3:0x36
	v_lshlrev_b32_e32 v196, 2, v5
	v_cmp_gt_u32_e64 s[6:7], 32, v3
	v_cmp_eq_u32_e64 s[8:9], 0, v3
	s_add_i32 s10, s10, 0
	v_lshlrev_b32_e32 v3, 1, v187
	v_mul_u32_u24_e32 v5, 0x440, v5
	v_add3_u32 v197, s10, v3, v5
	v_and_b32_e32 v3, 15, v1
	v_bfe_u32 v1, v1, 4, 2
	v_bitop3_b32 v23, v6, v8, 32 bitop3:0x36
	v_bitop3_b32 v24, v6, v8, 64 bitop3:0x36
	v_lshlrev_b32_e32 v162, 4, v3
	v_lshlrev_b32_e32 v8, 11, v1
	v_mov_b32_e32 v0, 0
	v_add_u32_e32 v195, 0, v10
	v_lshl_add_u32 v15, v193, 8, 0
	v_lshl_add_u32 v17, v194, 8, 0
	v_lshl_add_u32 v19, v187, 8, 0
	v_add_u32_e32 v5, s10, v162
	v_lshlrev_b32_e32 v6, 3, v3
	v_mul_u32_u24_e32 v3, 0x110, v1
	v_or_b32_e32 v10, 0x2000, v8
	v_or_b32_e32 v12, 0x4000, v8
	v_or_b32_e32 v14, 0x6000, v8
	v_or_b32_e32 v16, 0x8000, v8
	v_or_b32_e32 v18, 0xa000, v8
	v_or_b32_e32 v20, 0xc000, v8
	v_or_b32_e32 v22, 0xe000, v8
	s_lshl_b32 s25, s2, 8
	s_lshl_b32 s26, s52, 8
	v_mov_b32_e32 v163, v0
	s_lshl_b32 s27, s2, 4
	v_add_u32_e32 v198, 0xa0, v193
	v_add_u32_e32 v199, 0x80, v193
	v_lshlrev_b32_e32 v164, 1, v2
	v_lshlrev_b32_e32 v166, 1, v4
	v_add_u32_e32 v200, v7, v11
	v_add_u32_e32 v201, v13, v11
	v_add_u32_e32 v202, v15, v9
	v_add_u32_e32 v203, v17, v9
	v_add_u32_e32 v204, v19, v21
	v_add_u32_e32 v205, v19, v23
	v_add_u32_e32 v206, v19, v24
	v_add_u32_e32 v207, v19, v25
	v_add_u32_e32 v208, v19, v26
	v_add_u32_e32 v209, v19, v27
	v_add_u32_e32 v210, v19, v28
	v_add_u32_e32 v211, v19, v29
	v_lshlrev_b32_e32 v168, 1, v6
	s_mov_b64 s[16:17], 0x19800000
	v_add_u32_e32 v212, v5, v3
	v_lshlrev_b32_e32 v170, 1, v8
	v_lshlrev_b32_e32 v172, 1, v10
	v_lshlrev_b32_e32 v174, 1, v12
	v_lshlrev_b32_e32 v176, 1, v14
	v_lshlrev_b32_e32 v178, 1, v16
	v_lshlrev_b32_e32 v180, 1, v18
	v_lshlrev_b32_e32 v182, 1, v20
	v_lshlrev_b32_e32 v184, 1, v22
	v_mov_b32_e32 v213, 0x3000
	v_mov_b32_e32 v165, v0
	v_mov_b32_e32 v167, v0
	v_mbcnt_lo_u32_b32 v214, -1, 0
	s_mov_b32 s29, s3
	s_mov_b32 s30, s2
	s_movk_i32 s28, 0x200
	s_cmp_eq_u32 s99, 0
	s_cbranch_scc1 .Lattn_order_done
	s_and_b32 s26, s2, 7
	s_lshl_b32 s26, s26, 2
	s_lshr_b32 s28, s2, 3
	s_and_b32 s30, s28, 3
	s_add_i32 s26, s26, s30
	s_lshr_b32 s28, s28, 2
	s_lshl_b32 s28, s28, 4
	s_lshr_b32 s30, s26, 4
	s_lshl_b32 s30, s30, 8
	s_and_b32 s26, s26, 15
	s_add_i32 s30, s30, s26
	s_add_i32 s30, s30, s28
	s_lshl_b32 s29, s30, 3
	s_lshl_b32 s25, s30, 8
	s_lshl_b32 s27, s30, 4
	s_add_i32 s28, s30, 0x100
	s_mov_b32 s26, 0x8000

.LBB0_1349:
	s_setprio 0
	s_mov_b64 s[8:9], s[0:1]
	s_getreg_b32 s10, hwreg(HW_REG_XCC_ID, 0, 4)
	s_waitcnt vmcnt(0)
	s_barrier
	s_and_saveexec_b64 s[6:7], s[44:45]
	s_cbranch_execz .LBB0_1401
	s_cmp_eq_u32 s99, 0
	s_cbranch_scc1 .Lfb_skip_5
	s_load_dwordx2 s[8:9], s[0:1], 0x80
	s_and_b32 s10, s2, 7
	s_lshl_b32 s10, s10, 8
	s_add_i32 s10, s10, 0x1000
	s_lshr_b32 s11, s2, 3
	s_lshl_b32 s11, s11, 2
	v_mov_b32_e32 v1, s11
	v_mov_b32_e32 v0, 6
	s_mov_b32 s13, 0
	s_mov_b64 s[16:17], exec
	s_waitcnt lgkmcnt(0)
	s_add_u32 s8, s8, s10
	s_addc_u32 s9, s9, 0
	global_store_dword v1, v0, s[8:9]
	buffer_inv sc1
	s_mov_b64 exec, 0xffffffff
	v_mbcnt_lo_u32_b32 v4, -1, 0
	v_lshlrev_b32_e32 v4, 2, v4
	v_mov_b32_e32 v0, 6
